# P4 unit prologue: bias tables held in registers until the first interval's wait; tables-ready barrier only behind the importance pass
# baseline (speedup 1.0000x reference)
.LBB0_556:
	s_cmp_lg_u32 s84, -1
	s_cselect_b32 s0, s84, 0
	s_cselect_b32 s1, s85, 0
	v_mov_b32_e32 v4, s0
	v_mov_b32_e32 v5, s1
	v_mov_b32_e32 v4, 0x24240
	ds_read_b32 v3, v4
	s_mov_b64 s[0:1], -1
	s_waitcnt lgkmcnt(0)
	s_barrier
	v_readfirstlane_b32 s4, v3
	s_cmpk_gt_i32 s4, 0x5ff
	s_cbranch_scc1 .LBB0_555
	v_readlane_b32 s0, v243, 11
	v_mov_b32_e32 v192, v0
	v_readlane_b32 s1, v243, 12
	s_cmpk_gt_i32 s4, 0x1ff
	v_readfirstlane_b32 s25, v192
	s_nop 2
	global_load_dword v18, v2, s[0:1]
	s_cselect_b64 s[0:1], -1, 0
	s_add_i32 s5, s4, 0xfffffe00
	s_cmpk_lt_i32 s4, 0x200
	v_writelane_b32 v243, s0, 43
	s_cselect_b64 s[2:3], -1, 0
	v_cndmask_b32_e64 v3, 0, 1, s[2:3]
	v_writelane_b32 v243, s1, 44
	s_and_b64 s[0:1], s[2:3], exec
	s_cselect_b32 s6, s4, s5
	s_movk_i32 s0, 0x1d0
	s_and_b32 s26, s6, 1
	v_cmp_gt_i32_e32 vcc, s0, v192
	v_cmp_ne_u32_e64 s[4:5], 1, v3
	s_and_saveexec_b64 s[0:1], vcc
	s_cbranch_execz .Ltp_a
	s_and_b64 s[8:9], s[2:3], exec
	s_cselect_b32 s7, 8, 0
	s_lshl_b32 s8, s26, 2
	s_or_b32 s7, s8, s7
	s_mulk_i32 s7, 0x740
	v_readlane_b32 s8, v243, 9
	v_readlane_b32 s9, v243, 10
	s_add_u32 s8, s8, s7
	v_lshlrev_b32_e32 v4, 2, v192
	s_addc_u32 s9, s9, 0
	v_ashrrev_i32_e32 v5, 31, v4
	v_lshl_add_u64 v[6:7], v[4:5], 2, s[8:9]
	global_load_dwordx4 v[244:247], v[6:7], off
	s_and_b64 vcc, exec, s[4:5]
	s_cbranch_vccnz .Ltp_a
	s_mul_i32 s7, s26, 0x1d00
	v_readlane_b32 s8, v243, 9
	v_readlane_b32 s9, v243, 10
	s_add_u32 s8, s8, s7
	s_addc_u32 s9, s9, 0
	v_lshl_add_u64 v[10:11], v[4:5], 2, s[8:9]
	v_add_co_u32_e32 v10, vcc, 0x7000, v10
	s_nop 1
	v_addc_co_u32_e32 v11, vcc, 0, v11, vcc
	global_load_dwordx4 v[248:251], v[10:11], off offset:1024
.Ltp_a:
	s_or_b64 exec, exec, s[0:1]
	v_cmp_gt_i32_e32 vcc, 4, v192
	s_and_saveexec_b64 s[0:1], vcc
	s_cbranch_execz .Ltp_b
	s_lshl_b32 s7, s26, 2
	s_and_b64 s[8:9], s[2:3], exec
	s_movk_i32 s8, 0x2b88
	s_cselect_b32 s8, s8, 0x2b80
	s_or_b32 s7, s7, s8
	v_add_u32_e32 v4, s7, v192
	v_readlane_b32 s8, v243, 9
	v_ashrrev_i32_e32 v5, 31, v4
	v_readlane_b32 s9, v243, 10
	s_nop 1
	v_lshl_add_u64 v[4:5], v[4:5], 2, s[8:9]
	global_load_dword v252, v[4:5], off

.LBB0_604:
	v_readlane_b32 s92, v243, 26
	v_readlane_b32 s94, v243, 28
	v_readlane_b32 s96, v243, 30
	v_readlane_b32 s82, v243, 32
	v_readlane_b32 s84, v243, 34
	v_readlane_b32 s86, v243, 36
	v_readlane_b32 s88, v243, 38
	v_readlane_b32 s98, v243, 40
	v_readlane_b32 s91, v243, 25
	v_readlane_b32 s93, v243, 27
	v_readlane_b32 s95, v243, 29
	v_readlane_b32 s97, v243, 31
	v_readlane_b32 s83, v243, 33
	v_readlane_b32 s85, v243, 35
	v_readlane_b32 s87, v243, 37
	v_readlane_b32 s89, v243, 39
	v_readlane_b32 s99, v243, 41
	v_readlane_b32 s84, v243, 42
	s_movk_i32 s90, 0x60
	v_readlane_b32 s25, v243, 52
	v_readlane_b32 s26, v242, 41
	v_readlane_b32 s27, v242, 40
	v_readlane_b32 s24, v243, 53
	s_waitcnt lgkmcnt(0)
	s_barrier
.LBB0_605:
	s_and_b64 s[0:1], s[2:3], exec
	s_movk_i32 s0, 0xff
	v_readlane_b32 s1, v243, 48
	s_cselect_b32 s12, s0, 0x7f
	s_lshl_b32 s0, s26, 23
	s_lshl_b32 s1, s1, 19
	s_or_b32 s0, s1, s0
	s_add_u32 s11, s86, s0
	v_readlane_b32 s0, v243, 43
	v_readlane_b32 s1, v243, 44
	s_addc_u32 s19, s87, 0
	s_andn2_b64 vcc, exec, s[0:1]
	s_mov_b64 s[0:1], -1
	s_waitcnt lgkmcnt(0)
	s_cbranch_vccnz .LBB0_607
	v_readlane_b32 s0, v243, 47
	s_addk_i32 s0, 0xff80
	s_ashr_i32 s0, s0, 6
	v_readlane_b32 s1, v243, 51
	s_cmp_gt_i32 s1, 0
	s_cselect_b32 s10, s0, 0
	s_add_u32 s6, s11, 0x4000000
	s_addc_u32 s7, s19, 0
	s_add_u32 s8, s11, 0x5000000
	s_addc_u32 s9, s19, 0
	s_mov_b64 s[0:1], 0

.LBB0_620:
	s_add_i32 s24, s10, 2
	s_cmp_gt_i32 s24, s42
	s_cselect_b64 s[22:23], -1, 0
	s_and_b64 s[20:21], s[22:23], exec
	v_cndmask_b32_e64 v197, 0, 1, s[22:23]
	s_cselect_b32 s20, s10, s24
	s_and_b64 s[22:23], s[2:3], s[22:23]
	v_cndmask_b32_e64 v3, 0, 1, s[22:23]
	v_and_b32_e32 v4, 3, v192
	v_readfirstlane_b32 s48, v3
	v_lshrrev_b32_e32 v3, 2, v192
	v_lshrrev_b32_e32 v8, 1, v192
	v_lshlrev_b32_e32 v199, 2, v85
	v_and_or_b32 v4, v3, 4, v4
	v_bitop3_b32 v5, v85, v8, 7 bitop3:0x78
	v_and_or_b32 v3, v3, 3, v199
	v_lshlrev_b32_e32 v11, 4, v5
	v_lshlrev_b32_e32 v3, 7, v3
	v_and_or_b32 v5, v192, 8, v4
	v_bitop3_b32 v4, v4, v192, 8 bitop3:0x72
	v_lshl_or_b32 v201, v4, 3, v3
	v_add_u32_e32 v4, s27, v194
	v_lshl_or_b32 v200, v5, 3, v3
	v_ashrrev_i32_e32 v5, 31, v4
	v_sub_u32_e32 v3, v199, v194
	s_and_b64 s[22:23], s[2:3], exec
	v_lshlrev_b64 v[6:7], 7, v[4:5]
	v_add_u32_e32 v202, 0xbf, v3
	s_cselect_b32 s50, 3, 1
	s_lshl_b32 s53, s26, 2
	v_lshl_add_u64 v[6:7], s[86:87], 0, v[6:7]
	v_and_b32_e32 v8, 16, v8
	v_mov_b32_e32 v9, v2
	v_or_b32_e32 v3, 0x80, v84
	v_cmp_ne_u32_e32 vcc, 0, v84
	s_add_i32 s54, s1, s53
	v_lshl_add_u64 v[170:171], v[6:7], 0, v[8:9]
	s_sub_i32 s1, s33, 31
	v_mov_b64_e32 v[6:7], s[98:99]
	v_cndmask_b32_e32 v3, 0, v3, vcc
	s_or_b32 s51, s33, 31
	s_ashr_i32 s52, s25, 8
	s_ashr_i32 s55, s1, 4
	s_ashr_i32 s56, s33, 4
	s_add_i32 s57, s33, 0xfffffe01
	s_add_i32 s58, s33, 0xfffffe20
	s_add_i32 s59, s33, 0xffffff81
	s_add_i32 s60, s33, 0xffffffa0
	v_mad_i64_i32 v[172:173], s[22:23], v4, s90, v[6:7]
	s_add_i32 s61, s43, -1
	v_lshlrev_b32_e32 v6, 2, v3
	v_and_b32_e32 v3, 1, v202
	v_lshlrev_b64 v[4:5], 11, v[4:5]
	v_lshlrev_b32_e32 v10, 7, v86
	s_cmp_lt_u32 s25, 64
	v_mov_b32_e32 v7, v2
	v_cmp_eq_u32_e32 vcc, 1, v3
	v_lshl_add_u64 v[4:5], s[88:89], 0, v[4:5]
	s_mov_b32 s49, 1
	v_or_b32_e32 v198, v11, v10
	v_add_u32_e32 v203, 0xfffffe01, v194
	v_add_u32_e32 v204, 0xffffff81, v194
	s_cselect_b64 s[22:23], -1, 0
	v_lshl_add_u64 v[174:175], s[96:97], 0, v[6:7]
	v_bitop3_b32 v206, v11, 32, v10 bitop3:0x36
	v_bitop3_b32 v207, v11, 64, v10 bitop3:0x36
	v_bitop3_b32 v208, v11, s90, v10 bitop3:0x36
	v_cndmask_b32_e32 v209, 0, v191, vcc
	s_add_i32 s62, s50, -1
	s_add_i32 s63, s0, s53
	v_lshl_add_u64 v[176:177], v[4:5], 0, v[8:9]
	v_mov_b32_e32 v205, 2.0
	s_mov_b32 s64, 0
	s_waitcnt vmcnt(0)
	v_cmp_gt_i32_e32 vcc, 0x1d0, v192
	s_and_saveexec_b64 s[0:1], vcc
	s_cbranch_execz .Ltp_c
	v_lshl_add_u32 v3, v192, 4, 0
	v_add_u32_e32 v3, 0x20800, v3
	ds_write_b128 v3, v[244:247]
	s_and_b64 vcc, exec, s[4:5]
	s_cbranch_vccnz .Ltp_c
	ds_write_b128 v3, v[248:251] offset:7424
.Ltp_c:
	s_or_b64 exec, exec, s[0:1]
	v_cmp_gt_i32_e32 vcc, 4, v192
	s_and_saveexec_b64 s[0:1], vcc
	s_cbranch_execz .Ltp_d
	v_lshl_add_u32 v4, v192, 2, 0
	v_add_u32_e32 v4, 0x24200, v4
	ds_write_b32 v4, v252
.Ltp_d:
	s_or_b64 exec, exec, s[0:1]
	s_waitcnt lgkmcnt(0)
	s_branch .LBB0_622
